# loop-edge edit: sweep-2 far path carries its own copy of the tile head and loops back with one taken branch
# speedup vs baseline: 1.0013x; 1.0013x over previous
; template <bool DIFF>
; __device__ __forceinline__ void qkt(f32x16& a, f32x16& b, const char* Ks, const char* Qs, int krow, int r32, int hi) {
;   a = f32x16{}; b = f32x16{};
; #pragma unroll
;   for (int d = 0; d < 4; ++d) {
;     const int cb0 = (d * 16 + hi * 8) * 2, cb1 = ((d + 4) * 16 + hi * 8) * 2;
;     const bf16x8 k0 = *reinterpret_cast<const bf16x8*>(Ks + KSWZ(krow, cb0)), q0 = *reinterpret_cast<const bf16x8*>(Qs + KSWZ(r32, cb0));
;     const bf16x8 k1 = *reinterpret_cast<const bf16x8*>(Ks + KSWZ(krow, cb1)), q1 = *reinterpret_cast<const bf16x8*>(Qs + KSWZ(r32, cb1));
;     a = __builtin_amdgcn_mfma_f32_32x32x16_bf16(k0, q0, a, 0, 0, 0);
;     b = __builtin_amdgcn_mfma_f32_32x32x16_bf16(k1, q1, b, 0, 0, 0); }
;   if (!DIFF) {
; #pragma unroll
;     for (int r = 0; r < 16; ++r) a[r] += b[r]; }
; }
.Lsw2_near:
	ds_read_b128 v[64:67], v176
	ds_read_b128 v[68:71], v172 offset:36864
	ds_read_b128 v[72:75], v177
	ds_read_b128 v[76:79], v176 offset:8192
	s_waitcnt lgkmcnt(2)
	v_mfma_f32_32x32x16_bf16 v[112:127], v[64:67], v[68:71], 0
	ds_read_b128 v[64:67], v171 offset:36864
	ds_read_b128 v[128:131], v177 offset:8192
	s_waitcnt lgkmcnt(1)
	v_mfma_f32_32x32x16_bf16 v[96:111], v[72:75], v[64:67], 0
	ds_read_b128 v[72:75], v178
	ds_read_b128 v[132:135], v170 offset:36864
	ds_read_b128 v[80:83], v179
	ds_read_b128 v[136:139], v178 offset:8192
	ds_read_b128 v[140:143], v169 offset:36864
	ds_read_b128 v[192:195], v179 offset:8192
	s_waitcnt lgkmcnt(1)
	v_mfma_f32_32x32x16_bf16 v[96:111], v[80:83], v[140:143], v[96:111]
	v_mfma_f32_32x32x16_bf16 v[112:127], v[72:75], v[132:135], v[112:127]
	ds_read_b128 v[72:75], v180
	ds_read_b128 v[196:199], v168 offset:36864
	ds_read_b128 v[80:83], v181
	ds_read_b128 v[200:203], v180 offset:8192
	ds_read_b128 v[204:207], v167 offset:36864
	ds_read_b128 v[210:213], v181 offset:8192
	s_waitcnt lgkmcnt(1)
	v_mfma_f32_32x32x16_bf16 v[96:111], v[80:83], v[204:207], v[96:111]
	v_mfma_f32_32x32x16_bf16 v[112:127], v[72:75], v[196:199], v[112:127]
	ds_read_b128 v[72:75], v182
	ds_read_b128 v[214:217], v166 offset:36864
	ds_read_b128 v[80:83], v183
	ds_read_b128 v[218:221], v182 offset:8192
	ds_read_b128 v[222:225], v149 offset:36864
	ds_read_b128 v[226:229], v183 offset:8192
	s_waitcnt lgkmcnt(1)
	v_mfma_f32_32x32x16_bf16 v[96:111], v[80:83], v[222:225], v[96:111]
	v_mfma_f32_32x32x16_bf16 v[80:95], v[76:79], v[68:71], 0
	v_mfma_f32_32x32x16_bf16 v[112:127], v[72:75], v[214:217], v[112:127]
	v_mfma_f32_32x32x16_bf16 v[64:79], v[128:131], v[64:67], 0
	v_lshl_add_u64 v[128:129], v[150:151], 0, s[34:35]
	v_add_co_u32_e32 v130, vcc, s70, v128
	s_nop 1
	v_addc_co_u32_e32 v131, vcc, 0, v129, vcc
	v_mfma_f32_32x32x16_bf16 v[80:95], v[136:139], v[132:135], v[80:95]
	v_add_co_u32_e32 v132, vcc, s71, v128
	v_lshl_add_u64 v[136:137], v[152:153], 0, s[34:35]
	s_nop 0
	v_addc_co_u32_e32 v133, vcc, 0, v129, vcc
	v_add_co_u32_e32 v138, vcc, s72, v136
	v_mfma_f32_32x32x16_bf16 v[64:79], v[192:195], v[140:143], v[64:79]
	s_nop 0
	v_addc_co_u32_e32 v139, vcc, 0, v137, vcc
	v_add_co_u32_e32 v140, vcc, s73, v136
	global_load_dwordx4 v[128:131], v[130:131], off
	s_nop 0
	global_load_dwordx4 v[132:135], v[132:133], off
	v_addc_co_u32_e32 v141, vcc, 0, v137, vcc
	global_load_dwordx4 v[136:139], v[138:139], off
	s_nop 0
	global_load_dwordx4 v[140:143], v[140:141], off
	v_mfma_f32_32x32x16_bf16 v[80:95], v[200:203], v[196:199], v[80:95]
	v_mfma_f32_32x32x16_bf16 v[64:79], v[210:213], v[204:207], v[64:79]
	v_mfma_f32_32x32x16_bf16 v[80:95], v[218:221], v[214:217], v[80:95]
	s_waitcnt lgkmcnt(0)
	v_mfma_f32_32x32x16_bf16 v[64:79], v[226:229], v[222:225], v[64:79]
	s_cmpk_ge_i32 s93, 0x9f
	s_cbranch_scc1 .Lb2a_hi
	s_cmpk_le_i32 s93, 0xff41
	s_cbranch_scc1 .Lb2a_lo
	v_add3_u32 v192, v191, v173, s55
	v_med3_i32 v193, v192, 0, v163
	v_lshl_add_u32 v200, v193, 2, 0
	v_max_i32_e32 v193, -1, v192
	v_add_u32_e32 v193, 1, v193
	v_min_u32_e32 v193, 0x100, v193
	v_lshl_add_u32 v201, v193, 2, 0
	v_max_i32_e32 v193, -2, v192
	v_add_u32_e32 v193, 2, v193
	v_min_u32_e32 v193, 0x100, v193
	v_lshl_add_u32 v202, v193, 2, 0
	v_max_i32_e32 v193, -3, v192
	v_add_u32_e32 v193, 3, v193
	v_min_u32_e32 v193, 0x100, v193
	v_lshl_add_u32 v203, v193, 2, 0
	v_max_i32_e32 v193, -8, v192
	v_add_u32_e32 v193, 8, v193
	v_min_u32_e32 v193, 0x100, v193
	v_lshl_add_u32 v204, v193, 2, 0
	v_max_i32_e32 v193, -9, v192
	v_add_u32_e32 v193, 9, v193
	v_min_u32_e32 v193, 0x100, v193
	v_lshl_add_u32 v205, v193, 2, 0
	v_max_i32_e32 v193, -10, v192
	v_add_u32_e32 v193, 10, v193
	v_min_u32_e32 v193, 0x100, v193
	v_lshl_add_u32 v206, v193, 2, 0
	v_max_i32_e32 v193, -11, v192
	v_add_u32_e32 v193, 11, v193
	v_min_u32_e32 v193, 0x100, v193
	v_lshl_add_u32 v207, v193, 2, 0
	v_max_i32_e32 v193, -16, v192
	v_max_i32_e32 v194, 0xffffffef, v192
	v_max_i32_e32 v195, 0xffffffee, v192
	v_max_i32_e32 v196, 0xffffffed, v192
	v_max_i32_e32 v197, 0xffffffe8, v192
	v_max_i32_e32 v198, 0xffffffe7, v192
	v_max_i32_e32 v199, 0xffffffe6, v192
	v_add_u32_e32 v193, 16, v193
	v_add_u32_e32 v194, 17, v194
	v_add_u32_e32 v195, 18, v195
	v_add_u32_e32 v196, 19, v196
	v_add_u32_e32 v197, 24, v197
	v_add_u32_e32 v198, 25, v198
	v_add_u32_e32 v199, 26, v199
	v_max_i32_e32 v192, 0xffffffe5, v192
	v_min_u32_e32 v193, 0x100, v193
	v_min_u32_e32 v194, 0x100, v194
	v_min_u32_e32 v195, 0x100, v195
	v_min_u32_e32 v196, 0x100, v196
	v_min_u32_e32 v197, 0x100, v197
	v_min_u32_e32 v198, 0x100, v198
	v_min_u32_e32 v199, 0x100, v199
	v_add_u32_e32 v192, 27, v192
	v_lshl_add_u32 v193, v193, 2, 0
	v_lshl_add_u32 v194, v194, 2, 0
	v_lshl_add_u32 v195, v195, 2, 0
	v_lshl_add_u32 v196, v196, 2, 0
	v_lshl_add_u32 v197, v197, 2, 0
	v_lshl_add_u32 v198, v198, 2, 0
	v_lshl_add_u32 v199, v199, 2, 0
	v_min_u32_e32 v192, 0x100, v192
	v_lshl_add_u32 v209, v192, 2, 0
	ds_read_b32 v192, v193 offset:32768
	ds_read_b32 v193, v194 offset:32768
	ds_read_b32 v194, v195 offset:32768
	ds_read_b32 v195, v196 offset:32768
	ds_read_b32 v196, v197 offset:32768
	ds_read_b32 v197, v198 offset:32768
	ds_read_b32 v198, v199 offset:32768
	ds_read_b32 v199, v209 offset:32768
	ds_read_b32 v200, v200 offset:32768
	ds_read_b32 v201, v201 offset:32768
	ds_read_b32 v202, v202 offset:32768
	ds_read_b32 v203, v203 offset:32768
	ds_read_b32 v204, v204 offset:32768
	ds_read_b32 v205, v205 offset:32768
	ds_read_b32 v206, v206 offset:32768
	ds_read_b32 v207, v207 offset:32768
	s_waitcnt lgkmcnt(8)
	v_pk_add_f32 v[126:127], v[126:127], v[198:199]
	v_pk_add_f32 v[124:125], v[124:125], v[196:197]
	v_pk_add_f32 v[122:123], v[122:123], v[194:195]
	v_pk_add_f32 v[120:121], v[120:121], v[192:193]
	s_waitcnt lgkmcnt(0)
	v_pk_add_f32 v[118:119], v[118:119], v[206:207]
	v_pk_add_f32 v[116:117], v[116:117], v[204:205]
	v_pk_add_f32 v[114:115], v[114:115], v[202:203]
	v_pk_add_f32 v[112:113], v[112:113], v[200:201]
	v_pk_add_f32 v[110:111], v[110:111], v[198:199]
	v_pk_add_f32 v[108:109], v[108:109], v[196:197]
	v_pk_add_f32 v[106:107], v[106:107], v[194:195]
	v_pk_add_f32 v[104:105], v[104:105], v[192:193]
	v_pk_add_f32 v[102:103], v[102:103], v[206:207]
	v_pk_add_f32 v[100:101], v[100:101], v[204:205]
	v_pk_add_f32 v[98:99], v[98:99], v[202:203]
	v_pk_add_f32 v[96:97], v[96:97], v[200:201]
	v_mov_b32_e32 v192, 0
	s_branch .LBB0_318

; template <bool DIFF>
; __device__ __forceinline__ void qkt(f32x16& a, f32x16& b, const char* Ks, const char* Qs, int krow, int r32, int hi) {
;   a = f32x16{}; b = f32x16{};
; #pragma unroll
;   for (int d = 0; d < 4; ++d) {
;     const int cb0 = (d * 16 + hi * 8) * 2, cb1 = ((d + 4) * 16 + hi * 8) * 2;
;     const bf16x8 k0 = *reinterpret_cast<const bf16x8*>(Ks + KSWZ(krow, cb0)), q0 = *reinterpret_cast<const bf16x8*>(Qs + KSWZ(r32, cb0));
;     const bf16x8 k1 = *reinterpret_cast<const bf16x8*>(Ks + KSWZ(krow, cb1)), q1 = *reinterpret_cast<const bf16x8*>(Qs + KSWZ(r32, cb1));
;     a = __builtin_amdgcn_mfma_f32_32x32x16_bf16(k0, q0, a, 0, 0, 0);
;     b = __builtin_amdgcn_mfma_f32_32x32x16_bf16(k1, q1, b, 0, 0, 0); }
;   if (!DIFF) {
; #pragma unroll
;     for (int r = 0; r < 16; ++r) a[r] += b[r]; }
; }
; template <bool DIFF> ...
;     ...
;       BIAS_APPLY(t, 0, a0, b0, cb0);
;       { const float x1 = fmaf(cb0, C, e1), x2 = fmaf(cb0, C, e2);
; #pragma unroll
;       for (int r = 0; r < 16; ++r) a0[r] = __builtin_amdgcn_exp2f(fmaf(a0[r], C, x1));
;       if (DIFF) {
; #pragma unroll
;         for (int r = 0; r < 16; ++r) a0[r] = fmaf(nsg, __builtin_amdgcn_exp2f(fmaf(b0[r], C, x2)), a0[r]);
;       } }
.Lsw2f:
	ds_read_b128 v[64:67], v176
	ds_read_b128 v[68:71], v172 offset:36864
	ds_read_b128 v[72:75], v177
	ds_read_b128 v[76:79], v176 offset:8192
	s_waitcnt lgkmcnt(2)
	v_mfma_f32_32x32x16_bf16 v[112:127], v[64:67], v[68:71], 0
	ds_read_b128 v[64:67], v171 offset:36864
	ds_read_b128 v[128:131], v177 offset:8192
	s_waitcnt lgkmcnt(1)
	v_mfma_f32_32x32x16_bf16 v[96:111], v[72:75], v[64:67], 0
	ds_read_b128 v[72:75], v178
	ds_read_b128 v[132:135], v170 offset:36864
	ds_read_b128 v[80:83], v179
	ds_read_b128 v[136:139], v178 offset:8192
	ds_read_b128 v[140:143], v169 offset:36864
	ds_read_b128 v[192:195], v179 offset:8192
	s_waitcnt lgkmcnt(1)
	v_mfma_f32_32x32x16_bf16 v[96:111], v[80:83], v[140:143], v[96:111]
	v_mfma_f32_32x32x16_bf16 v[112:127], v[72:75], v[132:135], v[112:127]
	ds_read_b128 v[72:75], v180
	ds_read_b128 v[196:199], v168 offset:36864
	ds_read_b128 v[80:83], v181
	ds_read_b128 v[200:203], v180 offset:8192
	ds_read_b128 v[204:207], v167 offset:36864
	ds_read_b128 v[210:213], v181 offset:8192
	s_waitcnt lgkmcnt(1)
	v_mfma_f32_32x32x16_bf16 v[96:111], v[80:83], v[204:207], v[96:111]
	v_mfma_f32_32x32x16_bf16 v[112:127], v[72:75], v[196:199], v[112:127]
	ds_read_b128 v[72:75], v182
	ds_read_b128 v[214:217], v166 offset:36864
	ds_read_b128 v[80:83], v183
	ds_read_b128 v[218:221], v182 offset:8192
	ds_read_b128 v[222:225], v149 offset:36864
	ds_read_b128 v[226:229], v183 offset:8192
	s_waitcnt lgkmcnt(1)
	v_mfma_f32_32x32x16_bf16 v[96:111], v[80:83], v[222:225], v[96:111]
	v_mfma_f32_32x32x16_bf16 v[112:127], v[72:75], v[214:217], v[112:127]
	s_waitcnt lgkmcnt(0)
	v_mfma_f32_32x32x16_bf16 v[80:95], v[76:79], v[68:71], 0
	v_fmamk_f32 v235, v234, 0x3e38aa3b, v188
	v_fmamk_f32 v234, v234, 0x3e38aa3b, v187
	s_nop 8
	v_fmamk_f32 v112, v112, 0x3e38aa3b, v235
	v_fmamk_f32 v113, v113, 0x3e38aa3b, v235
	v_fmamk_f32 v114, v114, 0x3e38aa3b, v235
	v_fmamk_f32 v115, v115, 0x3e38aa3b, v235
	v_fmamk_f32 v116, v116, 0x3e38aa3b, v235
	v_fmamk_f32 v117, v117, 0x3e38aa3b, v235
	v_fmamk_f32 v96, v96, 0x3e38aa3b, v234
	v_fmamk_f32 v97, v97, 0x3e38aa3b, v234
	v_fmamk_f32 v98, v98, 0x3e38aa3b, v234
	v_fmamk_f32 v99, v99, 0x3e38aa3b, v234
	v_fmamk_f32 v100, v100, 0x3e38aa3b, v234
	v_fmamk_f32 v101, v101, 0x3e38aa3b, v234
	v_exp_f32_e32 v112, v112
	v_mfma_f32_32x32x16_bf16 v[64:79], v[128:131], v[64:67], 0
	v_exp_f32_e32 v113, v113
	v_exp_f32_e32 v114, v114
	v_exp_f32_e32 v115, v115
	v_exp_f32_e32 v116, v116
	v_exp_f32_e32 v117, v117
	v_fmamk_f32 v118, v118, 0x3e38aa3b, v235
	v_fmamk_f32 v119, v119, 0x3e38aa3b, v235
	v_fmamk_f32 v120, v120, 0x3e38aa3b, v235
	v_fmamk_f32 v121, v121, 0x3e38aa3b, v235
	v_fmamk_f32 v122, v122, 0x3e38aa3b, v235
	v_mfma_f32_32x32x16_bf16 v[80:95], v[136:139], v[132:135], v[80:95]
	v_fmamk_f32 v123, v123, 0x3e38aa3b, v235
	v_fmamk_f32 v124, v124, 0x3e38aa3b, v235
	v_fmamk_f32 v125, v125, 0x3e38aa3b, v235
	v_fmamk_f32 v126, v126, 0x3e38aa3b, v235
	v_fmac_f32_e32 v235, 0x3e38aa3b, v127
	v_exp_f32_e32 v96, v96
	v_exp_f32_e32 v97, v97
	v_exp_f32_e32 v98, v98
	v_exp_f32_e32 v99, v99
	v_exp_f32_e32 v100, v100
	v_exp_f32_e32 v101, v101
	v_mfma_f32_32x32x16_bf16 v[64:79], v[192:195], v[140:143], v[64:79]
	v_lshl_add_u64 v[128:129], v[150:151], 0, s[34:35]
	v_add_co_u32_e32 v130, vcc, s70, v128
	s_nop 1
	v_addc_co_u32_e32 v131, vcc, 0, v129, vcc
	v_add_co_u32_e32 v132, vcc, s71, v128
	v_lshl_add_u64 v[136:137], v[152:153], 0, s[34:35]
	s_nop 0
	v_addc_co_u32_e32 v133, vcc, 0, v129, vcc
	v_add_co_u32_e32 v138, vcc, s72, v136
	s_nop 1
	v_addc_co_u32_e32 v139, vcc, 0, v137, vcc
	v_add_co_u32_e32 v140, vcc, s73, v136
	global_load_dwordx4 v[128:131], v[130:131], off
	s_nop 0
	global_load_dwordx4 v[132:135], v[132:133], off
	v_addc_co_u32_e32 v141, vcc, 0, v137, vcc
	global_load_dwordx4 v[136:139], v[138:139], off
	s_nop 0
	global_load_dwordx4 v[140:143], v[140:141], off
	v_fmamk_f32 v102, v102, 0x3e38aa3b, v234
	v_fmamk_f32 v103, v103, 0x3e38aa3b, v234
	v_fmamk_f32 v104, v104, 0x3e38aa3b, v234
	v_fmamk_f32 v105, v105, 0x3e38aa3b, v234
	v_fmamk_f32 v106, v106, 0x3e38aa3b, v234
	v_fmamk_f32 v107, v107, 0x3e38aa3b, v234
	v_fmamk_f32 v108, v108, 0x3e38aa3b, v234
	v_fmamk_f32 v109, v109, 0x3e38aa3b, v234
	v_fmamk_f32 v110, v110, 0x3e38aa3b, v234
	v_fmac_f32_e32 v234, 0x3e38aa3b, v111
	v_exp_f32_e32 v118, v118
	v_exp_f32_e32 v119, v119
	v_exp_f32_e32 v120, v120
	v_mfma_f32_32x32x16_bf16 v[80:95], v[200:203], v[196:199], v[80:95]
	v_exp_f32_e32 v121, v121
	v_exp_f32_e32 v122, v122
	v_exp_f32_e32 v123, v123
	v_exp_f32_e32 v124, v124
	v_exp_f32_e32 v125, v125
	v_exp_f32_e32 v126, v126
	v_exp_f32_e32 v127, v235
	v_exp_f32_e32 v102, v102
	v_mfma_f32_32x32x16_bf16 v[64:79], v[210:213], v[204:207], v[64:79]
	v_exp_f32_e32 v103, v103
	v_exp_f32_e32 v104, v104
	v_exp_f32_e32 v105, v105
	v_exp_f32_e32 v106, v106
	v_exp_f32_e32 v107, v107
	v_exp_f32_e32 v108, v108
	v_exp_f32_e32 v109, v109
	v_exp_f32_e32 v110, v110
	v_mfma_f32_32x32x16_bf16 v[80:95], v[218:221], v[214:217], v[80:95]
	v_exp_f32_e32 v111, v234
	v_pk_fma_f32 v[96:97], v[144:145], v[96:97], v[112:113]
	v_pk_fma_f32 v[98:99], v[144:145], v[98:99], v[114:115]
	v_pk_fma_f32 v[100:101], v[144:145], v[100:101], v[116:117]
	v_pk_fma_f32 v[102:103], v[144:145], v[102:103], v[118:119]
	v_pk_fma_f32 v[104:105], v[144:145], v[104:105], v[120:121]
	v_pk_fma_f32 v[106:107], v[144:145], v[106:107], v[122:123]
	v_pk_fma_f32 v[108:109], v[144:145], v[108:109], v[124:125]
	v_mfma_f32_32x32x16_bf16 v[64:79], v[226:229], v[222:225], v[64:79]
	v_pk_fma_f32 v[110:111], v[144:145], v[110:111], v[126:127]
	v_cvt_pk_bf16_f32 v96, v96, v97
	v_cvt_pk_bf16_f32 v97, v98, v99
	v_cvt_pk_bf16_f32 v98, v100, v101
; #define SBAR() __builtin_amdgcn_sched_barrier(0)
; #define KWRITE() do { *reinterpret_cast<bf16x8*>(K_lds + kst0) = ks0; *reinterpret_cast<bf16x8*>(K_lds + kst1) = ks1; } while (0)
; #define VWRITE() do { *reinterpret_cast<bf16x8*>(V_lds + vst0) = vs0; *reinterpret_cast<bf16x8*>(V_lds + vst1) = vs1; } while (0)
; template <bool DIFF> ...
;     ...
;   for (int t = t_lo; t < t_hi; ++t) {
;     __syncthreads();
;     KWRITE(); VWRITE();
;     __syncthreads();
;     ...
;       PK4(a0, 0, pa0); PK4(a0, 8, pa1);
;       SBAR();
;       pv_step<0>(o, vb0, pa0); pv_step<1>(o, vb0, pa1);
;       SBAR();
;       BIAS_APPLY(t, 1, a1, b1, cb1);
;       { const float x1 = fmaf(cb1, C, e1), x2 = fmaf(cb1, C, e2);
; #pragma unroll
;       for (int r = 0; r < 16; ++r) a1[r] = __builtin_amdgcn_exp2f(fmaf(a1[r], C, x1));
;       if (DIFF) {
; #pragma unroll
;         for (int r = 0; r < 16; ++r) a1[r] = fmaf(nsg, __builtin_amdgcn_exp2f(fmaf(b1[r], C, x2)), a1[r]);
;       } }
;       PK4(a1, 0, pa2); PK4(a1, 8, pa3);
;       SBAR();
;       pv_step<2>(o, vb0, pa2); pv_step<3>(o, vb0, pa3);
	v_cvt_pk_bf16_f32 v99, v102, v103
	s_nop 0
	v_permlane32_swap_b32_e32 v96, v98
	v_cvt_pk_bf16_f32 v100, v104, v105
	v_cvt_pk_bf16_f32 v101, v106, v107
	v_cvt_pk_bf16_f32 v102, v108, v109
	v_cvt_pk_bf16_f32 v103, v110, v111
	v_permlane32_swap_b32_e32 v97, v99
	v_permlane32_swap_b32_e32 v100, v102
	v_permlane32_swap_b32_e32 v101, v103
	ds_read_b64_tr_b16 v[104:105], v146 offset:0
	ds_read_b64_tr_b16 v[106:107], v146 offset:0x800
	ds_read_b64_tr_b16 v[108:109], v146 offset:0x200
	ds_read_b64_tr_b16 v[110:111], v146 offset:0xa00
	ds_read_b64_tr_b16 v[112:113], v146 offset:0x400
	ds_read_b64_tr_b16 v[114:115], v146 offset:0xc00
	ds_read_b64_tr_b16 v[116:117], v146 offset:0x600
	ds_read_b64_tr_b16 v[118:119], v146 offset:0xe00
	ds_read_b64_tr_b16 v[238:239], v146 offset:0x1000
	ds_read_b64_tr_b16 v[240:241], v146 offset:0x1800
	ds_read_b64_tr_b16 v[242:243], v146 offset:0x1200
	ds_read_b64_tr_b16 v[244:245], v146 offset:0x1a00
	ds_read_b64_tr_b16 v[246:247], v146 offset:0x1400
	ds_read_b64_tr_b16 v[248:249], v146 offset:0x1c00
	ds_read_b64_tr_b16 v[120:121], v146 offset:0x1600
	ds_read_b64_tr_b16 v[122:123], v146 offset:0x1e00
	v_fmamk_f32 v237, v236, 0x3e38aa3b, v188
	v_fmamk_f32 v236, v236, 0x3e38aa3b, v187
	v_fmamk_f32 v80, v80, 0x3e38aa3b, v237
	v_fmamk_f32 v81, v81, 0x3e38aa3b, v237
	v_fmamk_f32 v82, v82, 0x3e38aa3b, v237
	v_fmamk_f32 v83, v83, 0x3e38aa3b, v237
	v_fmamk_f32 v84, v84, 0x3e38aa3b, v237
	v_fmamk_f32 v85, v85, 0x3e38aa3b, v237
	v_fmamk_f32 v86, v86, 0x3e38aa3b, v237
	v_fmamk_f32 v87, v87, 0x3e38aa3b, v237
	s_waitcnt lgkmcnt(0)
	v_mfma_f32_32x32x16_bf16 v[0:15], v[96:99], v[104:107], v[0:15]
	v_fmamk_f32 v88, v88, 0x3e38aa3b, v237
	v_fmamk_f32 v89, v89, 0x3e38aa3b, v237
	v_fmamk_f32 v90, v90, 0x3e38aa3b, v237
	v_fmamk_f32 v91, v91, 0x3e38aa3b, v237
	v_fmamk_f32 v92, v92, 0x3e38aa3b, v237
	v_fmamk_f32 v93, v93, 0x3e38aa3b, v237
	v_fmamk_f32 v94, v94, 0x3e38aa3b, v237
	v_fmac_f32_e32 v237, 0x3e38aa3b, v95
	v_fmamk_f32 v64, v64, 0x3e38aa3b, v236
	v_fmamk_f32 v65, v65, 0x3e38aa3b, v236
	v_fmamk_f32 v66, v66, 0x3e38aa3b, v236
	v_fmamk_f32 v67, v67, 0x3e38aa3b, v236
	v_fmamk_f32 v68, v68, 0x3e38aa3b, v236
	v_fmamk_f32 v69, v69, 0x3e38aa3b, v236
	v_fmamk_f32 v70, v70, 0x3e38aa3b, v236
	v_mfma_f32_32x32x16_bf16 v[16:31], v[96:99], v[108:111], v[16:31]
	v_fmamk_f32 v71, v71, 0x3e38aa3b, v236
	v_fmamk_f32 v72, v72, 0x3e38aa3b, v236
	v_fmamk_f32 v73, v73, 0x3e38aa3b, v236
	v_fmamk_f32 v74, v74, 0x3e38aa3b, v236
	v_fmamk_f32 v75, v75, 0x3e38aa3b, v236
	v_fmamk_f32 v76, v76, 0x3e38aa3b, v236
	v_fmamk_f32 v77, v77, 0x3e38aa3b, v236
	v_fmamk_f32 v78, v78, 0x3e38aa3b, v236
	v_fmac_f32_e32 v236, 0x3e38aa3b, v79
	v_exp_f32_e32 v80, v80
	v_exp_f32_e32 v81, v81
	v_exp_f32_e32 v82, v82
	v_mfma_f32_32x32x16_bf16 v[32:47], v[96:99], v[112:115], v[32:47]
	v_exp_f32_e32 v83, v83
	v_exp_f32_e32 v84, v84
	v_exp_f32_e32 v85, v85
	v_exp_f32_e32 v86, v86
	v_exp_f32_e32 v87, v87
	v_exp_f32_e32 v88, v88
	v_exp_f32_e32 v89, v89
	v_mfma_f32_32x32x16_bf16 v[48:63], v[96:99], v[116:119], v[48:63]
	v_exp_f32_e32 v90, v90
	v_exp_f32_e32 v91, v91
	v_exp_f32_e32 v92, v92
	v_exp_f32_e32 v93, v93
	v_exp_f32_e32 v94, v94
	v_exp_f32_e32 v95, v237
	v_exp_f32_e32 v64, v64
	v_mfma_f32_32x32x16_bf16 v[0:15], v[100:103], v[238:241], v[0:15]
	v_exp_f32_e32 v65, v65
	v_exp_f32_e32 v66, v66
	v_exp_f32_e32 v67, v67
	v_exp_f32_e32 v68, v68
	v_exp_f32_e32 v69, v69
	v_exp_f32_e32 v70, v70
	v_exp_f32_e32 v71, v71
	v_mfma_f32_32x32x16_bf16 v[16:31], v[100:103], v[242:245], v[16:31]
	v_exp_f32_e32 v72, v72
	v_exp_f32_e32 v73, v73
	v_exp_f32_e32 v74, v74
	v_exp_f32_e32 v75, v75
	v_exp_f32_e32 v76, v76
	v_exp_f32_e32 v77, v77
	v_exp_f32_e32 v78, v78
	v_mfma_f32_32x32x16_bf16 v[32:47], v[100:103], v[246:249], v[32:47]
	v_exp_f32_e32 v79, v236
	v_pk_fma_f32 v[64:65], v[144:145], v[64:65], v[80:81]
	v_pk_fma_f32 v[66:67], v[144:145], v[66:67], v[82:83]
	v_pk_fma_f32 v[68:69], v[144:145], v[68:69], v[84:85]
	v_pk_fma_f32 v[70:71], v[144:145], v[70:71], v[86:87]
	v_pk_fma_f32 v[72:73], v[144:145], v[72:73], v[88:89]
	v_pk_fma_f32 v[74:75], v[144:145], v[74:75], v[90:91]
	v_mfma_f32_32x32x16_bf16 v[48:63], v[100:103], v[120:123], v[48:63]
	v_pk_fma_f32 v[76:77], v[144:145], v[76:77], v[92:93]
	v_pk_fma_f32 v[78:79], v[144:145], v[78:79], v[94:95]
	v_cvt_pk_bf16_f32 v64, v64, v65
	v_cvt_pk_bf16_f32 v65, v66, v67
	v_cvt_pk_bf16_f32 v66, v68, v69
	v_cvt_pk_bf16_f32 v67, v70, v71
	v_cvt_pk_bf16_f32 v68, v72, v73
	v_cvt_pk_bf16_f32 v69, v74, v75
	v_cvt_pk_bf16_f32 v70, v76, v77
	v_cvt_pk_bf16_f32 v71, v78, v79
	v_permlane32_swap_b32_e32 v64, v66
	v_permlane32_swap_b32_e32 v65, v67
	v_permlane32_swap_b32_e32 v68, v70
	v_permlane32_swap_b32_e32 v69, v71
	ds_read_b64_tr_b16 v[72:73], v146 offset:0x2000
	ds_read_b64_tr_b16 v[74:75], v146 offset:0x2800
	ds_read_b64_tr_b16 v[76:77], v146 offset:0x2200
	ds_read_b64_tr_b16 v[78:79], v146 offset:0x2a00
	ds_read_b64_tr_b16 v[80:81], v146 offset:0x2400
	ds_read_b64_tr_b16 v[82:83], v146 offset:0x2c00
	ds_read_b64_tr_b16 v[84:85], v146 offset:0x2600
	ds_read_b64_tr_b16 v[86:87], v146 offset:0x2e00
	ds_read_b64_tr_b16 v[238:239], v146 offset:0x3000
	ds_read_b64_tr_b16 v[240:241], v146 offset:0x3800
	ds_read_b64_tr_b16 v[242:243], v146 offset:0x3200
	ds_read_b64_tr_b16 v[244:245], v146 offset:0x3a00
	ds_read_b64_tr_b16 v[246:247], v146 offset:0x3400
	ds_read_b64_tr_b16 v[248:249], v146 offset:0x3c00
	ds_read_b64_tr_b16 v[88:89], v146 offset:0x3600
	ds_read_b64_tr_b16 v[90:91], v146 offset:0x3e00
	s_waitcnt lgkmcnt(8)
	v_mfma_f32_32x32x16_bf16 v[0:15], v[64:67], v[72:75], v[0:15]
	v_mfma_f32_32x32x16_bf16 v[16:31], v[64:67], v[76:79], v[16:31]
	v_mfma_f32_32x32x16_bf16 v[32:47], v[64:67], v[80:83], v[32:47]
	v_mfma_f32_32x32x16_bf16 v[48:63], v[64:67], v[84:87], v[48:63]
	s_waitcnt lgkmcnt(0)
	v_mfma_f32_32x32x16_bf16 v[0:15], v[68:71], v[238:241], v[0:15]
	s_add_u32 s34, s34, 0x20000
	s_addc_u32 s35, s35, 0
	v_add_u32_e32 v173, 64, v173
	s_add_i32 s93, s93, 64
	s_cmp_eq_u32 s2, s34
	v_mfma_f32_32x32x16_bf16 v[16:31], v[68:71], v[242:245], v[16:31]
	v_mfma_f32_32x32x16_bf16 v[32:47], v[68:71], v[246:249], v[32:47]
	v_mfma_f32_32x32x16_bf16 v[48:63], v[68:71], v[88:91], v[48:63]
	s_cbranch_scc1 .LBB0_326
	s_barrier
	s_waitcnt vmcnt(3)
	ds_write_b128 v174, v[128:131]
	s_waitcnt vmcnt(2)
	ds_write_b128 v175, v[132:135]
	s_waitcnt vmcnt(1)
	ds_write_b128 v189, v[136:139] offset:16384
	s_waitcnt vmcnt(0)
	ds_write_b128 v190, v[140:143] offset:16384
	s_waitcnt lgkmcnt(0)
	s_barrier
	s_cmpk_ge_i32 s93, 0x9f
	s_cbranch_scc0 .Lsw2r_nothi
	v_mov_b32_e32 v234, v253
	v_mov_b32_e32 v236, v253
	s_branch .Lsw2f
.Lsw2r_nothi:
	s_cmpk_le_i32 s93, 0xff41
	s_cbranch_scc0 .Lsw2_near
	v_mov_b32_e32 v234, v252
	v_mov_b32_e32 v236, v252
	s_branch .Lsw2f
